# ml_k2 rewrite: all global loads and the previous chunk's output stores issued right after the barrier ahead of the MFMA stream, started 20us into the scan phase, L2 touch prefetch
# baseline (speedup 1.0000x reference)
.Lmk2_chunk:
	s_waitcnt vmcnt(2)
	ds_write_b128 v245, v[66:69]
	ds_write_b128 v245, v[74:77] offset:9216
	ds_write_b128 v245, v[82:85] offset:18432
	ds_write_b128 v245, v[90:93] offset:27648
	ds_write_b128 v245, v[70:73] offset:4608
	ds_write_b128 v245, v[78:81] offset:13824
	ds_write_b128 v245, v[86:89] offset:23040
	ds_write_b128 v245, v[94:97] offset:32256
	ds_write_b32 v251, v118
	v_mov_b32_e32 v104, v98
	v_mov_b32_e32 v105, v99
	v_mov_b32_e32 v106, v100
	v_mov_b32_e32 v107, v101
	v_mov_b32_e32 v108, v102
	v_mov_b32_e32 v109, v103
	v_cvt_pk_bf16_f32 v228, v2, v3
	v_cvt_pk_bf16_f32 v229, v4, v5
	v_cvt_pk_bf16_f32 v230, v6, v7
	v_cvt_pk_bf16_f32 v231, v8, v9
	v_cvt_pk_bf16_f32 v232, v10, v11
	v_cvt_pk_bf16_f32 v233, v12, v13
	v_cvt_pk_bf16_f32 v234, v14, v15
	v_cvt_pk_bf16_f32 v235, v16, v17
	v_max_f32_e32 v138, v119, v105
	v_sub_f32_e32 v139, v119, v138
	v_mul_f32_e32 v139, 0x3fb8aa3b, v139
	v_exp_f32_e32 v139, v139
	v_sub_f32_e32 v140, v108, v138
	v_mul_f32_e32 v140, 0x3fb8aa3b, v140
	v_exp_f32_e32 v140, v140
	v_add_f32_e32 v141, v138, v104
	v_mul_f32_e32 v141, 0xbfb8aa3b, v141
	v_exp_f32_e32 v141, v141
	v_max_f32_e32 v0, v119, v108
	v_sub_f32_e32 v186, v119, v0
	v_mul_f32_e32 v186, 0x3fb8aa3b, v186
	v_exp_f32_e32 v186, v186
	v_sub_f32_e32 v184, v108, v0
	v_mul_f32_e32 v184, 0x3fb8aa3b, v184
	v_exp_f32_e32 v184, v184
	v_add_f32_e32 v119, v109, v0
	s_waitcnt lgkmcnt(0)
	s_barrier
	s_cmpk_eq_u32 s2, 0
	s_cbranch_scc1 .Lmk2_nols
	global_store_dwordx2 v254, v[172:173], s[42:43]
	v_add_u32_e32 v120, 0x20000, v254
	global_store_dwordx2 v120, v[174:175], s[42:43]
	s_nop 0
	v_add_u32_e32 v120, 0x40000, v254
	global_store_dwordx2 v120, v[176:177], s[42:43]
	s_nop 0
	v_add_u32_e32 v120, 0x60000, v254
	global_store_dwordx2 v120, v[178:179], s[42:43]
	s_nop 0
	s_add_u32 s42, s42, 0x80000
	s_addc_u32 s43, s43, 0
.Lmk2_nols:
	global_load_dwordx4 v[66:69], v236, s[4:5]
	global_load_dwordx4 v[74:77], v242, s[6:7]
	global_load_dwordx4 v[82:85], v242, s[8:9]
	global_load_dwordx4 v[90:93], v242, s[38:39]
	global_load_dwordx4 v[70:73], v237, s[4:5]
	global_load_dwordx4 v[78:81], v243, s[6:7]
	global_load_dwordx4 v[86:89], v243, s[8:9]
	global_load_dwordx4 v[94:97], v243, s[38:39]
	global_load_dword v98, v244, s[40:41]
	global_load_dword v99, v244, s[40:41] offset:256
	global_load_dword v100, v244, s[40:41] offset:512
	global_load_dword v101, v244, s[40:41] offset:768
	global_load_dword v102, v1, s[40:41] offset:1024
	global_load_dword v103, v1, s[40:41] offset:252
	s_cmpk_lt_u32 s2, 30
	s_cselect_b32 s47, 0x80000, 0
	s_add_u32 s4, s4, s47
	s_addc_u32 s5, s5, 0
	s_cmpk_lt_u32 s2, 30
	s_cselect_b32 s47, 0x6000, 0
	s_cselect_b32 s48, 0x500, 0
	s_add_u32 s6, s6, s47
	s_addc_u32 s7, s7, 0
	s_add_u32 s8, s8, s47
	s_addc_u32 s9, s9, 0
	s_add_u32 s38, s38, s47
	s_addc_u32 s39, s39, 0
	s_add_u32 s40, s40, s48
	s_addc_u32 s41, s41, 0
	global_load_ubyte v125, v[188:189], off
	global_load_ubyte v125, v[190:191], off
	v_lshl_add_u64 v[188:189], v[188:189], 0, v[192:193]
	v_lshl_add_u64 v[190:191], v[190:191], 0, v[194:195]
	ds_read_b64 v[196:197], v246 offset:0
	ds_read_b64 v[198:199], v246 offset:32
	ds_read_b128 v[126:129], v249 offset:0
	ds_read_b128 v[164:167], v250 offset:0
	ds_read_b128 v[168:171], v250 offset:16
	ds_read_b64 v[200:201], v246 offset:2304
	ds_read_b64 v[202:203], v246 offset:2336
	ds_read_b64 v[204:205], v246 offset:4608
	ds_read_b64 v[206:207], v246 offset:4640
	ds_read_b64 v[208:209], v246 offset:6912
	ds_read_b64 v[210:211], v246 offset:6944
	s_waitcnt lgkmcnt(9)
	v_mfma_f32_16x16x32_bf16 v[18:21], v[228:231], v[196:199], 0
	ds_read_b128 v[130:133], v249 offset:16
	ds_read_b128 v[172:175], v250 offset:32
	ds_read_b128 v[176:179], v250 offset:48
	s_waitcnt lgkmcnt(9)
	v_and_b32_e32 v120, 0xffff0000, v126
	v_mul_f32_e32 v142, v165, v120
	v_lshlrev_b32_e32 v121, 16, v126
	v_fmac_f32_e32 v142, v164, v121
	v_lshlrev_b32_e32 v120, 16, v127
	v_fmac_f32_e32 v142, v166, v120
	v_and_b32_e32 v121, 0xffff0000, v127
	v_fmac_f32_e32 v142, v167, v121
	v_lshlrev_b32_e32 v120, 16, v128
	v_fmac_f32_e32 v142, v168, v120
	v_and_b32_e32 v121, 0xffff0000, v128
	v_fmac_f32_e32 v142, v169, v121
	v_lshlrev_b32_e32 v120, 16, v129
	v_fmac_f32_e32 v142, v170, v120
	v_and_b32_e32 v121, 0xffff0000, v129
	v_fmac_f32_e32 v142, v171, v121
	v_add_f32_e32 v143, 0, v142
	ds_read_b64 v[212:213], v246 offset:64
	ds_read_b64 v[214:215], v246 offset:96
	s_waitcnt lgkmcnt(9)
	v_mfma_f32_16x16x32_bf16 v[22:25], v[228:231], v[200:203], 0
	ds_read_b64 v[216:217], v246 offset:2368
	ds_read_b64 v[218:219], v246 offset:2400
	s_waitcnt lgkmcnt(9)
	v_mfma_f32_16x16x32_bf16 v[26:29], v[228:231], v[204:207], 0
	ds_read_b64 v[220:221], v246 offset:4672
	ds_read_b64 v[222:223], v246 offset:4704
	s_waitcnt lgkmcnt(9)
	v_mfma_f32_16x16x32_bf16 v[30:33], v[228:231], v[208:211], 0
	ds_read_b128 v[134:137], v249 offset:32
	ds_read_b128 v[164:167], v250 offset:64
	ds_read_b128 v[168:171], v250 offset:80
	s_waitcnt lgkmcnt(9)
	v_and_b32_e32 v120, 0xffff0000, v130
	v_mul_f32_e32 v142, v173, v120
	v_lshlrev_b32_e32 v121, 16, v130
	v_fmac_f32_e32 v142, v172, v121
	v_lshlrev_b32_e32 v120, 16, v131
	v_fmac_f32_e32 v142, v174, v120
	v_and_b32_e32 v121, 0xffff0000, v131
	v_fmac_f32_e32 v142, v175, v121
	v_lshlrev_b32_e32 v120, 16, v132
	v_fmac_f32_e32 v142, v176, v120
	v_and_b32_e32 v121, 0xffff0000, v132
	v_fmac_f32_e32 v142, v177, v121
	v_lshlrev_b32_e32 v120, 16, v133
	v_fmac_f32_e32 v142, v178, v120
	v_and_b32_e32 v121, 0xffff0000, v133
	v_fmac_f32_e32 v142, v179, v121
	v_add_f32_e32 v143, v143, v142
	ds_read_b64 v[224:225], v246 offset:6976
	ds_read_b64 v[226:227], v246 offset:7008
	s_waitcnt lgkmcnt(9)
	v_mfma_f32_16x16x32_bf16 v[18:21], v[232:235], v[212:215], v[18:21]
	ds_read_b128 v[110:113], v248 offset:27648
	ds_read_b128 v[196:199], v247 offset:9216
	s_waitcnt lgkmcnt(9)
	v_mfma_f32_16x16x32_bf16 v[22:25], v[232:235], v[216:219], v[22:25]
	ds_read_b128 v[200:203], v247 offset:11520
	s_waitcnt lgkmcnt(8)
	v_mfma_f32_16x16x32_bf16 v[26:29], v[232:235], v[220:223], v[26:29]
	ds_read_b128 v[126:129], v249 offset:48
	ds_read_b128 v[172:175], v250 offset:96
	ds_read_b128 v[176:179], v250 offset:112
	s_waitcnt lgkmcnt(8)
	v_and_b32_e32 v120, 0xffff0000, v134
	v_mul_f32_e32 v142, v165, v120
	v_lshlrev_b32_e32 v121, 16, v134
	v_fmac_f32_e32 v142, v164, v121
	v_lshlrev_b32_e32 v120, 16, v135
	v_fmac_f32_e32 v142, v166, v120
	v_and_b32_e32 v121, 0xffff0000, v135
	v_fmac_f32_e32 v142, v167, v121
	v_lshlrev_b32_e32 v120, 16, v136
	v_fmac_f32_e32 v142, v168, v120
	v_and_b32_e32 v121, 0xffff0000, v136
	v_fmac_f32_e32 v142, v169, v121
	v_lshlrev_b32_e32 v120, 16, v137
	v_fmac_f32_e32 v142, v170, v120
	v_and_b32_e32 v121, 0xffff0000, v137
	v_fmac_f32_e32 v142, v171, v121
	v_add_f32_e32 v143, v143, v142
	ds_read_b128 v[204:207], v247 offset:13824
	s_waitcnt lgkmcnt(7)
	v_mfma_f32_16x16x32_bf16 v[30:33], v[232:235], v[224:227], v[30:33]
	ds_read_b128 v[208:211], v247 offset:16128
	s_waitcnt lgkmcnt(6)
	v_mfma_f32_16x16x32_bf16 v[34:37], v[110:113], v[196:199], 0
	ds_read_b128 v[114:117], v248 offset:27712
	ds_read_b128 v[212:215], v247 offset:9280
	s_waitcnt lgkmcnt(7)
	v_mfma_f32_16x16x32_bf16 v[38:41], v[110:113], v[200:203], 0
	ds_read_b128 v[130:133], v249 offset:64
	ds_read_b128 v[164:167], v250 offset:128
	ds_read_b128 v[168:171], v250 offset:144
	s_waitcnt lgkmcnt(7)
	v_and_b32_e32 v120, 0xffff0000, v126
	v_mul_f32_e32 v142, v173, v120
	v_lshlrev_b32_e32 v121, 16, v126
	v_fmac_f32_e32 v142, v172, v121
	v_lshlrev_b32_e32 v120, 16, v127
	v_fmac_f32_e32 v142, v174, v120
	v_and_b32_e32 v121, 0xffff0000, v127
	v_fmac_f32_e32 v142, v175, v121
	v_lshlrev_b32_e32 v120, 16, v128
	v_fmac_f32_e32 v142, v176, v120
	v_and_b32_e32 v121, 0xffff0000, v128
	v_fmac_f32_e32 v142, v177, v121
	v_lshlrev_b32_e32 v120, 16, v129
	v_fmac_f32_e32 v142, v178, v120
	v_and_b32_e32 v121, 0xffff0000, v129
	v_fmac_f32_e32 v142, v179, v121
	v_add_f32_e32 v143, v143, v142
	ds_read_b128 v[216:219], v247 offset:11584
	s_waitcnt lgkmcnt(7)
	v_mfma_f32_16x16x32_bf16 v[42:45], v[110:113], v[204:207], 0
	ds_read_b128 v[220:223], v247 offset:13888
	s_waitcnt lgkmcnt(7)
	v_mfma_f32_16x16x32_bf16 v[46:49], v[110:113], v[208:211], 0
	ds_read_b128 v[224:227], v247 offset:16192
	s_waitcnt lgkmcnt(6)
	v_mfma_f32_16x16x32_bf16 v[34:37], v[114:117], v[212:215], v[34:37]
	ds_read_b128 v[134:137], v249 offset:80
	ds_read_b128 v[172:175], v250 offset:160
	ds_read_b128 v[176:179], v250 offset:176
	s_waitcnt lgkmcnt(6)
	v_and_b32_e32 v120, 0xffff0000, v130
	v_mul_f32_e32 v142, v165, v120
	v_lshlrev_b32_e32 v121, 16, v130
	v_fmac_f32_e32 v142, v164, v121
	v_lshlrev_b32_e32 v120, 16, v131
	v_fmac_f32_e32 v142, v166, v120
	v_and_b32_e32 v121, 0xffff0000, v131
	v_fmac_f32_e32 v142, v167, v121
	v_lshlrev_b32_e32 v120, 16, v132
	v_fmac_f32_e32 v142, v168, v120
	v_and_b32_e32 v121, 0xffff0000, v132
	v_fmac_f32_e32 v142, v169, v121
	v_lshlrev_b32_e32 v120, 16, v133
	v_fmac_f32_e32 v142, v170, v120
	v_and_b32_e32 v121, 0xffff0000, v133
	v_fmac_f32_e32 v142, v171, v121
	v_add_f32_e32 v143, v143, v142
	ds_read_b128 v[196:199], v247 offset:18432
	s_waitcnt lgkmcnt(6)
	v_mfma_f32_16x16x32_bf16 v[38:41], v[114:117], v[216:219], v[38:41]
	ds_read_b128 v[200:203], v247 offset:20736
	s_waitcnt lgkmcnt(6)
	v_mfma_f32_16x16x32_bf16 v[42:45], v[114:117], v[220:223], v[42:45]
	ds_read_b128 v[204:207], v247 offset:23040
	s_waitcnt lgkmcnt(6)
	v_mfma_f32_16x16x32_bf16 v[46:49], v[114:117], v[224:227], v[46:49]
	ds_read_b128 v[126:129], v249 offset:96
	ds_read_b128 v[164:167], v250 offset:192
	ds_read_b128 v[168:171], v250 offset:208
	s_waitcnt lgkmcnt(6)
	v_and_b32_e32 v120, 0xffff0000, v134
	v_mul_f32_e32 v142, v173, v120
	v_lshlrev_b32_e32 v121, 16, v134
	v_fmac_f32_e32 v142, v172, v121
	v_lshlrev_b32_e32 v120, 16, v135
	v_fmac_f32_e32 v142, v174, v120
	v_and_b32_e32 v121, 0xffff0000, v135
	v_fmac_f32_e32 v142, v175, v121
	v_lshlrev_b32_e32 v120, 16, v136
	v_fmac_f32_e32 v142, v176, v120
	v_and_b32_e32 v121, 0xffff0000, v136
	v_fmac_f32_e32 v142, v177, v121
	v_lshlrev_b32_e32 v120, 16, v137
	v_fmac_f32_e32 v142, v178, v120
	v_and_b32_e32 v121, 0xffff0000, v137
	v_fmac_f32_e32 v142, v179, v121
	v_add_f32_e32 v143, v143, v142
	ds_read_b128 v[208:211], v247 offset:25344
	s_waitcnt lgkmcnt(6)
	v_mfma_f32_16x16x32_bf16 v[50:53], v[196:199], v[110:113], 0
	ds_read_b128 v[212:215], v247 offset:18496
	s_waitcnt lgkmcnt(6)
	v_mfma_f32_16x16x32_bf16 v[54:57], v[200:203], v[110:113], 0
	ds_read_b128 v[216:219], v247 offset:20800
	s_waitcnt lgkmcnt(6)
	v_mfma_f32_16x16x32_bf16 v[58:61], v[204:207], v[110:113], 0
	ds_read_b128 v[130:133], v249 offset:112
	ds_read_b128 v[172:175], v250 offset:224
	ds_read_b128 v[176:179], v250 offset:240
	s_waitcnt lgkmcnt(6)
	v_and_b32_e32 v120, 0xffff0000, v126
	v_mul_f32_e32 v142, v165, v120
	v_lshlrev_b32_e32 v121, 16, v126
	v_fmac_f32_e32 v142, v164, v121
	v_lshlrev_b32_e32 v120, 16, v127
	v_fmac_f32_e32 v142, v166, v120
	v_and_b32_e32 v121, 0xffff0000, v127
	v_fmac_f32_e32 v142, v167, v121
	v_lshlrev_b32_e32 v120, 16, v128
	v_fmac_f32_e32 v142, v168, v120
	v_and_b32_e32 v121, 0xffff0000, v128
	v_fmac_f32_e32 v142, v169, v121
	v_lshlrev_b32_e32 v120, 16, v129
	v_fmac_f32_e32 v142, v170, v120
	v_and_b32_e32 v121, 0xffff0000, v129
	v_fmac_f32_e32 v142, v171, v121
	v_add_f32_e32 v143, v143, v142
	ds_read_b128 v[220:223], v247 offset:23104
	s_waitcnt lgkmcnt(6)
	v_mfma_f32_16x16x32_bf16 v[62:65], v[208:211], v[110:113], 0
	ds_read_b128 v[224:227], v247 offset:25408
	s_waitcnt lgkmcnt(6)
	v_mfma_f32_16x16x32_bf16 v[50:53], v[212:215], v[114:117], v[50:53]
	s_waitcnt lgkmcnt(5)
	v_mfma_f32_16x16x32_bf16 v[54:57], v[216:219], v[114:117], v[54:57]
	s_waitcnt lgkmcnt(2)
	v_and_b32_e32 v120, 0xffff0000, v130
	v_mul_f32_e32 v142, v173, v120
	v_lshlrev_b32_e32 v121, 16, v130
	v_fmac_f32_e32 v142, v172, v121
	v_lshlrev_b32_e32 v120, 16, v131
	v_fmac_f32_e32 v142, v174, v120
	v_and_b32_e32 v121, 0xffff0000, v131
	v_fmac_f32_e32 v142, v175, v121
	v_lshlrev_b32_e32 v120, 16, v132
	v_fmac_f32_e32 v142, v176, v120
	v_and_b32_e32 v121, 0xffff0000, v132
	v_fmac_f32_e32 v142, v177, v121
	v_lshlrev_b32_e32 v120, 16, v133
	v_fmac_f32_e32 v142, v178, v120
	v_and_b32_e32 v121, 0xffff0000, v133
	v_fmac_f32_e32 v142, v179, v121
	v_add_f32_e32 v143, v143, v142
	s_waitcnt lgkmcnt(1)
	v_mfma_f32_16x16x32_bf16 v[58:61], v[220:223], v[114:117], v[58:61]
	s_waitcnt lgkmcnt(0)
	v_mfma_f32_16x16x32_bf16 v[62:65], v[224:227], v[114:117], v[62:65]
	v_mul_f32_e32 v143, v139, v143
	v_fmac_f32_e32 v143, v106, v140
	v_max_f32_e64 v143, |v143|, v141
	v_rcp_f32_e32 v143, v143
	s_nop 0
	v_mul_f32_e32 v120, v139, v143
	v_mul_f32_e32 v121, v140, v143
	ds_write_b64 v253, v[120:121]
	s_waitcnt lgkmcnt(0)
	ds_read_b64 v[164:165], v252 offset:0
	ds_read_b64 v[166:167], v252 offset:128
	ds_read_b64 v[168:169], v252 offset:256
	ds_read_b64 v[170:171], v252 offset:384
	s_waitcnt lgkmcnt(0)
	v_mul_f32_e32 v180, v34, v165
	v_fmac_f32_e32 v180, v18, v164
	v_mul_f32_e32 v181, v35, v165
	v_fmac_f32_e32 v181, v19, v164
	v_mul_f32_e32 v182, v36, v165
	v_fmac_f32_e32 v182, v20, v164
	v_mul_f32_e32 v183, v37, v165
	v_fmac_f32_e32 v183, v21, v164
	v_cvt_pk_bf16_f32 v172, v180, v181
	v_cvt_pk_bf16_f32 v173, v182, v183
	v_mul_f32_e32 v180, v38, v167
	v_fmac_f32_e32 v180, v22, v166
	v_mul_f32_e32 v181, v39, v167
	v_fmac_f32_e32 v181, v23, v166
	v_mul_f32_e32 v182, v40, v167
	v_fmac_f32_e32 v182, v24, v166
	v_mul_f32_e32 v183, v41, v167
	v_fmac_f32_e32 v183, v25, v166
	v_cvt_pk_bf16_f32 v174, v180, v181
	v_cvt_pk_bf16_f32 v175, v182, v183
	v_mul_f32_e32 v180, v42, v169
	v_fmac_f32_e32 v180, v26, v168
	v_mul_f32_e32 v181, v43, v169
	v_fmac_f32_e32 v181, v27, v168
	v_mul_f32_e32 v182, v44, v169
	v_fmac_f32_e32 v182, v28, v168
	v_mul_f32_e32 v183, v45, v169
	v_fmac_f32_e32 v183, v29, v168
	v_cvt_pk_bf16_f32 v176, v180, v181
	v_cvt_pk_bf16_f32 v177, v182, v183
	v_mul_f32_e32 v180, v46, v171
	v_fmac_f32_e32 v180, v30, v170
	v_mul_f32_e32 v181, v47, v171
	v_fmac_f32_e32 v181, v31, v170
	v_mul_f32_e32 v182, v48, v171
	v_fmac_f32_e32 v182, v32, v170
	v_mul_f32_e32 v183, v49, v171
	v_fmac_f32_e32 v183, v33, v170
	v_cvt_pk_bf16_f32 v178, v180, v181
	v_cvt_pk_bf16_f32 v179, v182, v183
	v_pk_mul_f32 v[50:51], v[184:185], v[50:51] op_sel_hi:[0,1]
	v_pk_mul_f32 v[52:53], v[184:185], v[52:53] op_sel_hi:[0,1]
	v_pk_mul_f32 v[54:55], v[184:185], v[54:55] op_sel_hi:[0,1]
	v_pk_mul_f32 v[56:57], v[184:185], v[56:57] op_sel_hi:[0,1]
	v_pk_mul_f32 v[58:59], v[184:185], v[58:59] op_sel_hi:[0,1]
	v_pk_mul_f32 v[60:61], v[184:185], v[60:61] op_sel_hi:[0,1]
	v_pk_mul_f32 v[62:63], v[184:185], v[62:63] op_sel_hi:[0,1]
	v_pk_mul_f32 v[64:65], v[184:185], v[64:65] op_sel_hi:[0,1]
	v_pk_fma_f32 v[2:3], v[2:3], v[186:187], v[50:51] op_sel_hi:[1,0,1]
	v_pk_fma_f32 v[4:5], v[4:5], v[186:187], v[52:53] op_sel_hi:[1,0,1]
	v_pk_fma_f32 v[6:7], v[6:7], v[186:187], v[54:55] op_sel_hi:[1,0,1]
	v_pk_fma_f32 v[8:9], v[8:9], v[186:187], v[56:57] op_sel_hi:[1,0,1]
	v_pk_fma_f32 v[10:11], v[10:11], v[186:187], v[58:59] op_sel_hi:[1,0,1]
	v_pk_fma_f32 v[12:13], v[12:13], v[186:187], v[60:61] op_sel_hi:[1,0,1]
	v_pk_fma_f32 v[14:15], v[14:15], v[186:187], v[62:63] op_sel_hi:[1,0,1]
	v_pk_fma_f32 v[16:17], v[16:17], v[186:187], v[64:65] op_sel_hi:[1,0,1]
	v_mul_f32_e32 v120, v118, v186
	v_mul_f32_e32 v121, v107, v184
	v_add_f32_e32 v118, v120, v121
	s_barrier
	s_add_u32 s2, s2, 1
	s_cmpk_lt_u32 s2, 32
	s_cbranch_scc1 .Lmk2_chunk
.Lmk2_done:
	global_store_dwordx2 v254, v[172:173], s[42:43]
	v_add_u32_e32 v120, 0x20000, v254
	global_store_dwordx2 v120, v[174:175], s[42:43]
	s_nop 0
	v_add_u32_e32 v120, 0x40000, v254
	global_store_dwordx2 v120, v[176:177], s[42:43]
	s_nop 0
	v_add_u32_e32 v120, 0x60000, v254
	global_store_dwordx2 v120, v[178:179], s[42:43]
	s_nop 0
	s_add_u32 s42, s42, 0x80000
	s_addc_u32 s43, s43, 0
	v_readlane_b32 s47, v239, 53
	s_lshl_b32 s47, s47, 3
	s_add_u32 s47, s47, s45
	s_lshl_b32 s47, s47, 2
	s_add_u32 s47, s47, s44
	s_lshl_b32 s48, s47, 14
	s_add_u32 s48, s48, 0x4850000
	s_add_u32 s42, s24, s48
	s_addc_u32 s43, s25, 0
	v_and_b32_e32 v120, 63, v144
	v_lshrrev_b32_e32 v121, 6, v144
	v_and_b32_e32 v142, 15, v120
	v_lshrrev_b32_e32 v143, 4, v120
	v_lshlrev_b32_e32 v142, 2, v142
	v_lshl_add_u32 v142, v121, 6, v142
	v_lshl_add_u32 v142, v143, 10, v142
	global_store_dword v142, v2, s[42:43] offset:0
	global_store_dword v142, v3, s[42:43] offset:256
	global_store_dword v142, v4, s[42:43] offset:512
	global_store_dword v142, v5, s[42:43] offset:768
	v_add_u32_e32 v142, 0x1000, v142
	global_store_dword v142, v6, s[42:43] offset:0
	global_store_dword v142, v7, s[42:43] offset:256
	global_store_dword v142, v8, s[42:43] offset:512
	global_store_dword v142, v9, s[42:43] offset:768
	v_add_u32_e32 v142, 0x1000, v142
	global_store_dword v142, v10, s[42:43] offset:0
	global_store_dword v142, v11, s[42:43] offset:256
	global_store_dword v142, v12, s[42:43] offset:512
	global_store_dword v142, v13, s[42:43] offset:768
	v_add_u32_e32 v142, 0x1000, v142
	global_store_dword v142, v14, s[42:43] offset:0
	global_store_dword v142, v15, s[42:43] offset:256
	global_store_dword v142, v16, s[42:43] offset:512
	global_store_dword v142, v17, s[42:43] offset:768
	s_lshl_b32 s48, s47, 8
	s_add_u32 s48, s48, 0x4950000
	s_add_u32 s42, s24, s48
	s_addc_u32 s43, s25, 0
	v_cmp_gt_u32_e32 vcc, 64, v144
	s_and_saveexec_b64 s[0:1], vcc
	global_store_dword v244, v118, s[42:43]
	s_lshl_b32 s48, s47, 2
	s_add_u32 s48, s48, 0x4954000
	s_add_u32 s42, s24, s48
	s_addc_u32 s43, s25, 0
	v_cmp_eq_u32_e32 vcc, 0, v144
	s_and_b64 exec, exec, vcc
	global_store_dword v1, v119, s[42:43]
	s_mov_b64 exec, s[0:1]
	s_waitcnt vmcnt(0)
	s_mov_b64 s[0:1], 0
